# conv constants in SGPRs, prologue weight-conversion loop prefetch fix
# baseline (speedup 1.0000x reference)
; __device__ __forceinline__ unsigned pk2(float lo, float hi) { unsigned r; asm("v_cvt_pk_bf16_f32 %0, %1, %2" : "=v"(r) : "v"(lo), "v"(hi)); return r; }
; __device__ __forceinline__ void cvt_to_lds(int tid, const f32x4 (&v)[2], float* scr) {
;     const int n4 = (tid & 15) * 4, kk0 = tid >> 4;
; #pragma unroll
;     for (int i = 0; i < 2; ++i) { float* d = scr + (kk0 + 32 * i) * 65 + n4; d[0] = v[i][0]; d[1] = v[i][1]; d[2] = v[i][2]; d[3] = v[i][3]; }
; }
; __device__ __forceinline__ void cvt_store(const CvtJob& jb, int tid, const float* scr) {
;     const int nkt = jb.K / 64, nb = jb.tile / nkt, kb = jb.tile % nkt, n0 = nb * 64, k0 = kb * 64;
;     const int nl = tid >> 3, kc = tid & 7; const float* sp = scr + (kc * 8) * 65 + nl;
;     u32x4 o; o.x = pk2(sp[0], sp[65]); o.y = pk2(sp[2 * 65], sp[3 * 65]); o.z = pk2(sp[4 * 65], sp[5 * 65]); o.w = pk2(sp[6 * 65], sp[7 * 65]);
;     *(u32x4*)(jb.Wt + (size_t)(n0 + nl) * jb.ldw + k0 + kc * 8) = o;
; __device__ __forceinline__ void convert_layer_weights(const Params& p, uchar* sm, int i, bool mixer, bool ffn) {
;     ...
;     f32x4 cur[2], nxt[2];
;     int it = bid;
;     if (it < n_all) cvt_load(job(it), tid, cur);
.LBB0_50:
	s_or_b64 exec, exec, s[4:5]
	s_load_dwordx8 s[4:11], s[0:1], 0x80
	s_movk_i32 s2, 0x104
	v_lshlrev_b32_e32 v2, 3, v4
	v_lshl_add_u32 v3, v1, 2, 0
	v_mul_lo_u32 v5, v20, s2
	s_waitcnt lgkmcnt(0)
	s_add_u32 s18, s10, 0x1e9c000
	s_addc_u32 s19, s11, 0
	v_ashrrev_i32_e32 v22, 3, v4
	v_and_b32_e32 v2, 56, v2
	s_add_u32 s20, s10, 0xecc000
	v_mul_u32_u24_e32 v4, 0x104, v2
	v_lshlrev_b32_e32 v6, 2, v22
	v_mov_b32_e32 v19, 0
	v_add_u32_e32 v24, v3, v5
	s_addc_u32 s21, s11, 0
	s_mov_b32 s3, 0
	v_add3_u32 v23, 0, v4, v6
	s_add_i32 s22, s17, 0xfffffc00
	s_movk_i32 s23, 0x3ff
	s_movk_i32 s24, 0x440
	v_add_u32_e32 v25, 0x2080, v24
	v_add_u32_e32 v26, 0x2088, v24
	v_lshlrev_b32_e32 v18, 1, v2
	v_mov_b32_e32 v27, 0x580
	s_waitcnt vmcnt(0)
	v_mov_b32_e32 v6, v14
	v_mov_b32_e32 v2, v10
	v_mov_b32_e32 v3, v11
	v_mov_b32_e32 v4, v12
	v_mov_b32_e32 v5, v13
	v_mov_b32_e32 v7, v15
	v_mov_b32_e32 v8, v16
	v_mov_b32_e32 v9, v17
	s_branch .LBB0_53

; __device__ __forceinline__ void cvt_store(const CvtJob& jb, int tid, const float* scr) {
;     const int nkt = jb.K / 64, nb = jb.tile / nkt, kb = jb.tile % nkt, n0 = nb * 64, k0 = kb * 64;
;     const int nl = tid >> 3, kc = tid & 7; const float* sp = scr + (kc * 8) * 65 + nl;
;     u32x4 o; o.x = pk2(sp[0], sp[65]); o.y = pk2(sp[2 * 65], sp[3 * 65]); o.z = pk2(sp[4 * 65], sp[5 * 65]); o.w = pk2(sp[6 * 65], sp[7 * 65]);
;     *(u32x4*)(jb.Wt + (size_t)(n0 + nl) * jb.ldw + k0 + kc * 8) = o;
; }
; __device__ __forceinline__ void convert_layer_weights(const Params& p, uchar* sm, int i, bool mixer, bool ffn) {
;     float* scr = (float*)sm;
;     const int j = i >> 1, bid = opaque_bid(), tid = opaque_tid();
;     const int T_AWIN = (3072 / 64) * 16, T_AWOUT = 16 * 16, T_MWIN = (MIN_NP / 64) * 16, T_MWOUT = 16 * 32, T_FWIN = (5632 / 64) * 16, T_FWOUT = 16 * 44;
;     const bool conv = (i & 1) == 0;
;     const int t_in = conv ? T_AWIN : T_MWIN, t_out = conv ? T_AWOUT : T_MWOUT;
;     const int n_mix = mixer ? t_in + t_out : 0, n_ffn = ffn ? T_FWIN + T_FWOUT : 0, n_all = n_mix + n_ffn;
;     auto job = [&](int it) -> CvtJob {
;         int r = it;
;         if (r < n_mix) {
;             if (conv) {
;                 if (r < t_in) return CvtJob{p.a_w_in + (size_t)j * 1024 * 3072, (bf16_t*)(p.ws + WS_WMIX), nullptr, 1024, 3072, LDW1, 3, r};
;                 return CvtJob{p.a_w_out + (size_t)j * 1024 * 1024, (bf16_t*)(p.ws + WS_WMIX + OFF_W2), nullptr, 1024, 1024, LDW1, 0, r - t_in};
;             }
;             if (r < t_in) return CvtJob{p.m_w_in + (size_t)j * 1024 * MIN_N, (bf16_t*)(p.ws + WS_WMIX), nullptr, 1024, MIN_N, LDW1, 0, r};
;             return CvtJob{p.m_w_out + (size_t)j * 2048 * 1024, (bf16_t*)(p.ws + WS_WMIX + OFF_W2), p.m_norm_g + (size_t)j * DI, 2048, 1024, LDW2, 0, r - t_in};
;         }
;         r -= n_mix;
;         if (r < T_FWIN) return CvtJob{p.f_w_in + (size_t)i * 1024 * 5632, (bf16_t*)(p.ws + WS_WFFN), nullptr, 1024, 5632, LDW1, 1, r};
;         return CvtJob{p.f_w_out + (size_t)i * 2816 * 1024, (bf16_t*)(p.ws + WS_WFFN + OFF_F2), nullptr, 2816, 1024, 2816, 0, r - T_FWIN};
;     };
;     f32x4 cur[2], nxt[2];
;     int it = bid;
;     if (it < n_all) cvt_load(job(it), tid, cur);
;     for (; it < n_all; it += gridDim.x) {
;         const CvtJob jb = job(it);
;         cvt_to_lds(tid, cur, scr);
.LBB0_52:
	s_abs_i32 s2, s25
	v_cvt_f32_u32_e32 v10, s2
	s_sub_i32 s12, 0, s2
	s_abs_i32 s11, s26
	s_xor_b32 s10, s26, s25
	v_rcp_iflag_f32_e32 v10, v10
	s_ashr_i32 s10, s10, 31
	s_waitcnt lgkmcnt(0)
	s_barrier
	v_mul_f32_e32 v10, 0x4f7ffffe, v10
	v_cvt_u32_f32_e32 v10, v10
	v_add_u32_e32 v16, 0x400, v23
	v_readfirstlane_b32 s13, v10
	s_mul_i32 s12, s12, s13
	s_mul_hi_u32 s12, s13, s12
	s_add_i32 s13, s13, s12
	s_mul_hi_u32 s12, s11, s13
	s_mul_i32 s13, s12, s2
	s_sub_i32 s11, s11, s13
	s_add_i32 s14, s12, 1
	s_sub_i32 s13, s11, s2
	s_cmp_ge_u32 s11, s2
	s_cselect_b32 s12, s14, s12
	s_cselect_b32 s11, s13, s11
	s_add_i32 s13, s12, 1
	ds_read2_b32 v[10:11], v23 offset1:65
	ds_read2_b32 v[12:13], v23 offset0:130 offset1:195
	s_cmp_ge_u32 s11, s2
	ds_read2_b32 v[14:15], v16 offset0:4 offset1:69
	ds_read2_b32 v[16:17], v16 offset0:134 offset1:199
	s_cselect_b32 s2, s13, s12
	s_xor_b32 s2, s2, s10
	s_sub_i32 s2, s2, s10
	s_waitcnt lgkmcnt(3)
	v_cvt_pk_bf16_f32 v10, v10, v11
	s_waitcnt lgkmcnt(2)
	v_cvt_pk_bf16_f32 v11, v12, v13
	s_waitcnt lgkmcnt(1)
	v_cvt_pk_bf16_f32 v12, v14, v15
	v_lshl_add_u32 v14, s2, 6, v22
	s_mul_i32 s10, s2, s25
	v_ashrrev_i32_e32 v15, 31, v14
	s_sub_i32 s10, s26, s10
	s_waitcnt lgkmcnt(0)
	v_cvt_pk_bf16_f32 v13, v16, v17
	v_mul_lo_u32 v16, s6, v15
	v_mul_lo_u32 v17, s7, v14
	v_mad_u64_u32 v[14:15], s[6:7], s6, v14, 0
	s_lshl_b32 s10, s10, 6
	v_add3_u32 v15, v15, v16, v17
	v_lshl_add_u64 v[14:15], v[14:15], 1, s[4:5]
	s_ashr_i32 s11, s10, 31
	v_lshl_add_u64 v[14:15], s[10:11], 1, v[14:15]
	v_lshl_add_u64 v[14:15], v[14:15], 0, v[18:19]
	global_store_dwordx4 v[14:15], v[10:13], off
	s_and_b64 vcc, exec, s[8:9]
	s_barrier
	s_cbranch_vccnz .LBB0_75

; __device__ __forceinline__ void convert_layer_weights(const Params& p, uchar* sm, int i, bool mixer, bool ffn) {
;     ...
;     for (; it < n_all; it += gridDim.x) {
;         const CvtJob jb = job(it);
;         cvt_to_lds(tid, cur, scr);
;         if (it + (int)gridDim.x < n_all) cvt_load(job(it + gridDim.x), tid, nxt);
.LBB0_57:
	s_add_i32 s22, s94, s22
	s_add_i32 s17, s17, s94
	s_add_i32 s29, s22, 0x400
	s_cmpk_gt_i32 s29, 0xc3f
	s_cselect_b64 s[8:9], -1, 0
	s_and_b64 vcc, exec, s[8:9]
	s_waitcnt vmcnt(0)
	v_mov_b32_e32 v14, v6
	v_mov_b32_e32 v10, v2
	v_mov_b32_e32 v11, v3
	v_mov_b32_e32 v12, v4
	v_mov_b32_e32 v13, v5
	v_mov_b32_e32 v15, v7
	v_mov_b32_e32 v16, v8
	v_mov_b32_e32 v17, v9
	ds_write2_b32 v24, v10, v11 offset1:1
	ds_write2_b32 v24, v12, v13 offset0:2 offset1:3
	ds_write2_b32 v25, v14, v15 offset1:1
	ds_write2_b32 v26, v16, v17 offset1:1
	s_cbranch_vccnz .LBB0_52
	s_cmpk_gt_i32 s29, 0x3ff
	s_mov_b64 s[14:15], -1
	s_cbranch_scc0 .LBB0_61
	s_cmpk_lt_u32 s22, 0x580
	s_cbranch_scc1 .LBB0_64
	s_load_dwordx8 s[36:43], s[0:1], 0x80
	s_add_i32 s27, s17, 0xfffff680
	s_movk_i32 s2, 0x400
	s_mov_b32 s28, 44
	s_mov_b64 s[12:13], 0
	s_waitcnt lgkmcnt(0)
	s_mov_b64 s[10:11], s[38:39]
	s_mov_b64 s[14:15], 0

; __device__ __forceinline__ void phase_ssd(const Params& p, uchar* sm, int j, bf16_t* zx, const float* dtraw, float* ssqb) {
;     const int tid = opaque_tid(), w = tid >> 6, lane = tid & 63, l15 = lane & 15, quad = lane >> 4;
;     const float* convw = p.m_conv_w + (size_t)j * 4 * CONVD; const float* convb = p.m_conv_b + (size_t)j * CONVD;
;     const int c8 = tid & 15, lp = tid >> 4;
;     const int chl = w * 16, rl = w >> 2;
;     float* dtL = (float*)(sm + L_DT); float* csL = (float*)(sm + L_CS); float* e1L = (float*)(sm + L_E1); float* e2L = (float*)(sm + L_E2);
;     for (int item = opaque_bid(); item < 256; item += gridDim.x) {
;         const int bl = item >> 4, g = item & 7, hp = (item >> 3) & 1;
;         const int headA = g * 4 + hp * 2;
;         const int xch = g * 256 + hp * 128 + c8 * 8;
;         float a_coef = 0.f, dtb = 0.f;
;         const bool tabw = (w == 1 || w == 3); const int th = w >> 1;
;         if (tabw) { a_coef = -__expf(p.m_a_log[j * 32 + headA + th]); dtb = p.m_dt_bias[j * 32 + headA + th]; }
;         const float dskip = p.m_d[j * 32 + headA + (c8 >> 3)];
;         f32x4 st[8];
; #pragma unroll
;         for (int n = 0; n < 8; ++n) st[n] = (f32x4){0.f, 0.f, 0.f, 0.f};
;         const int bch = 2048 + g * 128 + c8 * 8, cch = 3072 + g * 128 + c8 * 8;
;         const int swz = 4 * (c8 >> 1);
;         u32x4 rx[5], rb[5], rc[5];
;         {
;             float* wl = (float*)(sm + LDS_WL);
;             if (tid < 480) { const int t = tid / 160, k = (tid % 160) >> 5, c4 = tid & 31;
;                 const int ch = (t == 0 ? g * 256 + hp * 128 : (t == 1 ? 2048 + g * 128 : 3072 + g * 128)) + c4 * 4;
;                 *(f32x4*)(wl + (t * 5 + k) * 128 + c4 * 4) = *(const f32x4*)((k < 4 ? convw + (size_t)k * CONVD : convb) + ch); }
;             __syncthreads();
;         }
;         const float* wlx = (const float*)(sm + LDS_WL) + c8 * 8; const float* wlb = wlx + 5 * 128; const float* wlc = wlx + 10 * 128;
;         const int toff = (2 * lp) * LDZ + c8 * 8;
;         const int colx = g * 256 + hp * 128, colb = 2048 + g * 128, colc = 3072 + g * 128;
;         { const bf16_t* zb = zx + (size_t)bl * SEQ * LDZ;
;           load_raw(zb + 2048 + colx, toff, true, 2 * lp, rx); load_raw(zb + 2048 + colb, toff, true, 2 * lp, rb); load_raw(zb + 2048 + colc, toff, true, 2 * lp, rc);
;         }
;         float dtr = 0.f;
.LBB0_423:
	s_mov_b32 s98, 0xbfb8aa3b
	s_mov_b32 s99, 0xbfb8aa3b
	s_mov_b32 s100, 1.0
	s_mov_b32 s101, 1.0
	v_mov_b32_e32 v1, v136
	s_mov_b32 s82, s68
	s_cmpk_gt_i32 s82, 0xff
	s_cbranch_scc1 .LBB0_482
	s_waitcnt vmcnt(0)
	v_and_b32_e32 v2, 0xffffff40, v1
	v_cmp_eq_u32_e64 s[6:7], 64, v2
	v_cmp_ne_u32_e64 s[8:9], 64, v2
	v_ashrrev_i32_e32 v158, 7, v1
	v_readlane_b32 s0, v255, 37
	v_bfe_u32 v2, v1, 3, 1
	s_movk_i32 s1, 0xa0
	v_add_u32_e32 v157, s0, v158
	v_or_b32_e32 v184, s0, v2
	s_movk_i32 s0, 0x1e0
	v_cmp_gt_i32_e64 s[10:11], s0, v1
	s_mov_b32 s0, 0x66666667
	v_mul_hi_i32 v2, v1, s0
	v_lshrrev_b32_e32 v3, 31, v2
	v_ashrrev_i32_e32 v2, 6, v2
	v_add_u32_e32 v12, v2, v3
	v_mul_lo_u32 v2, v12, s1
	v_add_u32_e32 v3, 0x9f, v1
	s_movk_i32 s0, 0x13f
	v_sub_u32_e32 v2, v1, v2
	v_cmp_gt_u32_e64 s[12:13], s0, v3
	v_add_u32_e32 v3, 0xffffff60, v1
	v_ashrrev_i32_e32 v2, 5, v2
	v_cmp_gt_u32_e64 s[14:15], s1, v3
	v_lshlrev_b32_e32 v3, 2, v1
	v_and_b32_e32 v185, 0x7c, v3
	v_ashrrev_i32_e32 v3, 31, v2
	v_readlane_b32 s0, v255, 35
	v_lshlrev_b64 v[4:5], 14, v[2:3]
	v_readlane_b32 s1, v255, 36
	v_cmp_gt_i32_e32 vcc, 4, v2
	v_and_b32_e32 v9, 15, v1
	v_lshl_add_u64 v[4:5], s[0:1], 0, v[4:5]
	v_readlane_b32 s0, v255, 34
	v_ashrrev_i32_e32 v10, 4, v1
	v_lshlrev_b32_e32 v7, 1, v1
	v_mov_b32_e32 v3, s0
	v_readlane_b32 s0, v255, 33
	v_cndmask_b32_e32 v161, v3, v5, vcc
	v_lshlrev_b32_e32 v5, 5, v9
	v_mov_b32_e32 v3, s0
	v_cndmask_b32_e32 v160, v3, v4, vcc
	v_lshl_add_u32 v3, v12, 2, v12
	v_add_lshl_u32 v2, v3, v2, 9
	v_lshlrev_b32_e32 v3, 2, v185
	v_readlane_b32 s0, v255, 10
	s_movk_i32 s5, 0x110
	v_ashrrev_i32_e32 v6, 6, v1
	v_add3_u32 v186, s0, v2, v3
	v_mul_lo_u32 v3, v10, s56
	v_add_u32_e32 v187, s0, v5
	v_lshl_or_b32 v162, v9, 3, v3
	v_bitop3_b32 v3, v7, v10, 28 bitop3:0x6c
	s_movk_i32 s0, 0x220
	v_lshlrev_b32_e32 v2, 1, v10
	v_lshl_add_u32 v12, v3, 2, 0
	v_mul_lo_u32 v3, v10, s0
	v_add_u32_e32 v13, 0, v3
	v_or_b32_e32 v3, 1, v2
	v_mul_lo_u32 v4, v3, s5
	v_add_u32_e32 v15, 0, v4
	v_lshlrev_b32_e32 v4, 1, v6
	v_and_b32_e32 v16, 2, v4
	v_lshlrev_b32_e32 v4, 4, v158
	v_or_b32_e32 v7, v4, v9
	v_and_b32_e32 v156, 63, v1
	v_mul_lo_u32 v7, v7, s5
	v_bfe_u32 v11, v1, 4, 2
	v_add_u32_e32 v17, 0, v7
	s_add_i32 s0, 0, 0x1a000
	v_lshlrev_b32_e32 v7, 2, v156
	v_lshl_or_b32 v18, v11, 2, v4
	v_mov_b32_e32 v4, s0
	v_lshl_add_u32 v19, v9, 2, s0
	v_lshl_or_b32 v7, v158, 8, v7
	v_readlane_b32 s1, v255, 11
	v_readlane_b32 s0, v255, 12
	v_readlane_b32 s24, v255, 13
	v_readlane_b32 s25, v255, 14
	v_add_u32_e32 v189, s1, v7
	v_add_u32_e32 v190, s0, v7
	v_add_u32_e32 v191, s24, v7
	v_add_u32_e32 v192, s25, v7
	v_and_b32_e32 v7, 3, v6
	v_ashrrev_i32_e32 v21, 2, v1
	v_lshl_or_b32 v20, v7, 4, v9
	v_and_b32_e32 v21, 0xffffffc0, v21
	v_or_b32_e32 v22, v20, v21
	v_cmp_lt_u32_e64 s[22:23], 1, v7
	v_lshlrev_b32_e32 v7, 2, v21
	v_lshlrev_b32_e32 v194, 3, v11
	v_lshlrev_b32_e32 v195, 5, v11
	s_movk_i32 s4, 0x90
	v_or_b32_e32 v26, 1, v16
	v_lshlrev_b32_e32 v8, 4, v6
	v_lshl_add_u32 v193, v22, 2, s0
	v_add3_u32 v196, s0, v7, v195
	v_mad_u32_u24 v197, v20, s5, v4
	v_mul_lo_u32 v4, v22, s4
	s_movk_i32 s0, 0x1100
	v_lshl_or_b32 v25, v16, 4, v9
	v_lshl_or_b32 v27, v26, 4, v9
	v_lshl_add_u32 v16, v16, 6, v19
	v_lshl_add_u32 v19, v26, 6, v19
	v_or_b32_e32 v26, 4, v194
	v_or_b32_e32 v29, 36, v194
	v_add_u32_e32 v198, s57, v4
	v_mul_lo_u32 v4, v6, s0
	v_mul_u32_u24_e32 v199, 0x110, v9
	v_readlane_b32 s0, v255, 15
	v_or_b32_e32 v6, v8, v9
	v_cmp_gt_u32_e64 s[28:29], v26, v20
	v_or_b32_e32 v26, 5, v194
	v_cmp_gt_u32_e64 s[46:47], v29, v20
	v_or_b32_e32 v29, 33, v194
	v_add3_u32 v200, s0, v4, v199
	v_add_u32_e32 v22, s24, v7
	v_mul_lo_u32 v4, v6, s4
	v_add3_u32 v201, s1, v7, v195
	v_add3_u32 v202, s25, v7, v195
	v_bfrev_b32_e32 v7, 0.5
	v_cmp_gt_u32_e64 s[34:35], v26, v20
	v_or_b32_e32 v26, 2, v194
	v_cmp_gt_u32_e64 s[48:49], v29, v20
	v_or_b32_e32 v29, 37, v194
	v_add_u32_e32 v4, 0, v4
	v_bitop3_b32 v7, v1, -4, v7 bitop3:0xc8
	s_movk_i32 s0, 0xff74
	v_cmp_gt_u32_e64 s[36:37], v26, v20
	v_or_b32_e32 v26, 6, v194
	v_cmp_gt_u32_e64 s[50:51], v29, v20
	v_or_b32_e32 v29, 34, v194
	v_add_u32_e32 v203, s24, v7
	v_mad_u64_u32 v[6:7], s[0:1], v6, s0, v[4:5]
	v_cmp_gt_u32_e64 s[38:39], v26, v20
	v_or_b32_e32 v26, 3, v194
	v_cmp_gt_u32_e64 s[52:53], v29, v20
	v_or_b32_e32 v29, 38, v194
	v_and_b32_e32 v188, 48, v1
	s_movk_i32 s0, 0x420
	v_cmp_gt_u32_e64 s[40:41], v26, v20
	v_or_b32_e32 v26, 7, v194
	v_cmp_gt_u32_e64 s[54:55], v29, v20
	v_or_b32_e32 v29, 35, v194
	v_add_u32_e32 v23, s57, v188
	v_mul_lo_u32 v7, v10, s0
	s_movk_i32 s0, 0x210
	v_cmp_gt_u32_e64 s[42:43], v26, v20
	v_or_b32_e32 v26, 32, v194
	v_cmp_gt_u32_e64 s[56:57], v29, v20
	v_or_b32_e32 v29, 39, v194
	v_or_b32_e32 v21, v21, v9
	v_mul_lo_u32 v3, v3, s0
	v_cmp_gt_u32_e64 s[26:27], v194, v20
	v_cmp_lt_u32_e64 s[30:31], v194, v20
	v_lshlrev_b32_e32 v28, 2, v26
	v_cmp_gt_u32_e64 s[44:45], v26, v20
	v_cmp_gt_u32_e64 s[58:59], v29, v20
	v_lshlrev_b32_e32 v20, 1, v26
	v_or_b32_e32 v26, 16, v9
	v_ashrrev_i32_e32 v163, 31, v162
	v_cmp_lt_i32_e64 s[16:17], 1, v10
	v_cmp_lt_i32_e64 s[18:19], 0, v10
	v_cmp_lt_i32_e64 s[20:21], -1, v10
	v_lshlrev_b32_e32 v14, 4, v9
	v_add_u32_e32 v7, 0, v7
	v_add_u32_e32 v10, 0, v3
	v_cmp_eq_u32_e64 s[24:25], 0, v9
	v_ashrrev_i32_e32 v3, 31, v2
	v_mul_u32_u24_e32 v24, 0x480, v9
	v_mul_u32_u24_e32 v25, 0x110, v25
	v_add_u32_e32 v204, 0, v188
	v_mul_u32_u24_e32 v27, 0x110, v27
	v_mul_lo_u32 v18, v18, s5
	v_mul_u32_u24_e32 v26, 0x110, v26
	v_bitop3_b32 v29, v8, v1, 48 bitop3:0x78
	v_bitop3_b32 v8, v188, v8, 64 bitop3:0x36
	v_mul_lo_u32 v21, v21, s4
	v_mad_u32_u24 v205, v9, s4, 0
	v_bitop3_b32 v9, v1, 16, 48 bitop3:0x6c
	v_bitop3_b32 v30, v1, 32, 48 bitop3:0x6c
	v_bitop3_b32 v1, v1, 48, v1 bitop3:0xc
	v_mul_u32_u24_e32 v11, 0x840, v11
	v_mov_b32_e32 v31, 0x1e81e000
	v_mov_b32_e32 v159, v0
	v_lshl_or_b32 v164, v156, 7, v31
	v_mov_b32_e32 v165, v0
	v_lshlrev_b64 v[166:167], 6, v[2:3]
	v_lshlrev_b64 v[168:169], 1, v[162:163]
	v_add_u32_e32 v206, v12, v24
	v_add_u32_e32 v207, v13, v14
	v_add_u32_e32 v208, v15, v14
	v_add_u32_e32 v209, v17, v188
	v_add_u32_e32 v210, v204, v25
	v_add_u32_e32 v211, v204, v27
	v_add_u32_e32 v212, v16, v18
	v_add_u32_e32 v213, v19, v18
	v_add_u32_e32 v214, v197, v28
	v_add_u32_e32 v215, v198, v20
	v_add_u32_e32 v216, v204, v26
	v_add_u32_e32 v217, v22, v188
	v_add_u32_e32 v218, v4, v29
	v_add_u32_e32 v219, v4, v8
	v_add_u32_e32 v220, v23, v21
	v_add_u32_e32 v221, v205, v9
	v_add_u32_e32 v222, v205, v30
	v_add_u32_e32 v223, v205, v1
	v_add_u32_e32 v224, v6, v11
	v_add_u32_e32 v225, v7, v5
	v_add_u32_e32 v226, v10, v5
	s_mov_b32 s77, s82
	s_branch .LBB0_426

; __device__ __forceinline__ unsigned pk2(float lo, float hi) { unsigned r; asm("v_cvt_pk_bf16_f32 %0, %1, %2" : "=v"(r) : "v"(lo), "v"(hi)); return r; }
; __device__ __forceinline__ float silu_f(float v) { return v * __builtin_amdgcn_rcpf(1.f + __expf(-v)); }
; __device__ __forceinline__ void conv_rows(const u32x4 (&rawp)[5], const float* wl, float (&o0)[8], float (&o1)[8]) {
;     float raw[5][8];
; #pragma unroll
;     for (int q = 0; q < 5; ++q) unpack8(rawp[q], raw[q]);
; #pragma unroll
;     for (int h = 0; h < 2; ++h) {
;         const f32x4 bv = *(const f32x4*)(wl + 4 * 128 + h * 4);
;         f32x4 a0 = bv, a1 = bv;
; #pragma unroll
;         for (int k = 0; k < 4; ++k) { const f32x4 wv = *(const f32x4*)(wl + k * 128 + h * 4);
; #pragma unroll
;             for (int i = 0; i < 4; ++i) { a0[i] += wv[i] * raw[k][h * 4 + i]; a1[i] += wv[i] * raw[k + 1][h * 4 + i]; } }
; #pragma unroll
;         for (int i = 0; i < 4; ++i) { o0[h * 4 + i] = silu_f(a0[i]); o1[h * 4 + i] = silu_f(a1[i]); }
;         __builtin_amdgcn_sched_barrier(0);
;     }
; }
; __device__ __forceinline__ void phase_ssd(const Params& p, uchar* sm, int j, bf16_t* zx, const float* dtraw, float* ssqb) {
;     ...
;             conv_rows(rx, wlx, xo0, xo1);
;             __builtin_amdgcn_sched_barrier(0);
; #pragma unroll
;             for (int i = 0; i < 8; ++i) *(unsigned*)(sm + L_XT + (c8 * 8 + i) * RS_T + ((lp ^ swz) * 4)) = pk2(xo0[i], xo1[i]);
.LBB0_466:
	ds_read_b128 v[132:135], v187 offset:2048
	ds_read_b128 v[96:99], v187 offset:0
	ds_read_b128 v[120:123], v187 offset:512
	ds_read_b128 v[124:127], v187 offset:1024
	ds_read_b128 v[128:131], v187 offset:1536
	s_nop 0
	v_lshlrev_b32_e32 v100, 16, v4
	v_and_b32_e32 v101, 0xffff0000, v4
	v_lshlrev_b32_e32 v118, 16, v5
	v_and_b32_e32 v119, 0xffff0000, v5
	s_waitcnt lgkmcnt(3)
	v_pk_fma_f32 v[144:145], v[96:97], v[100:101], v[132:133]
	v_pk_fma_f32 v[178:179], v[98:99], v[118:119], v[134:135]
	v_lshlrev_b32_e32 v100, 16, v8
	v_and_b32_e32 v101, 0xffff0000, v8
	v_lshlrev_b32_e32 v118, 16, v9
	v_and_b32_e32 v119, 0xffff0000, v9
	s_waitcnt lgkmcnt(2)
	v_pk_fma_f32 v[144:145], v[120:121], v[100:101], v[144:145]
	v_pk_fma_f32 v[178:179], v[122:123], v[118:119], v[178:179]
	v_pk_fma_f32 v[180:181], v[96:97], v[100:101], v[132:133]
	v_pk_fma_f32 v[230:231], v[98:99], v[118:119], v[134:135]
	v_lshlrev_b32_e32 v100, 16, v12
	v_and_b32_e32 v101, 0xffff0000, v12
	v_lshlrev_b32_e32 v118, 16, v13
	v_and_b32_e32 v119, 0xffff0000, v13
	s_waitcnt lgkmcnt(1)
	v_pk_fma_f32 v[144:145], v[124:125], v[100:101], v[144:145]
	v_pk_fma_f32 v[178:179], v[126:127], v[118:119], v[178:179]
	v_pk_fma_f32 v[180:181], v[120:121], v[100:101], v[180:181]
	v_pk_fma_f32 v[230:231], v[122:123], v[118:119], v[230:231]
	v_lshlrev_b32_e32 v100, 16, v16
	v_and_b32_e32 v101, 0xffff0000, v16
	v_lshlrev_b32_e32 v118, 16, v17
	v_and_b32_e32 v119, 0xffff0000, v17
	s_waitcnt lgkmcnt(0)
	v_pk_fma_f32 v[144:145], v[128:129], v[100:101], v[144:145]
	v_pk_fma_f32 v[178:179], v[130:131], v[118:119], v[178:179]
	v_pk_fma_f32 v[180:181], v[124:125], v[100:101], v[180:181]
	v_pk_fma_f32 v[230:231], v[126:127], v[118:119], v[230:231]
	v_lshlrev_b32_e32 v100, 16, v24
	v_and_b32_e32 v101, 0xffff0000, v24
	v_lshlrev_b32_e32 v118, 16, v25
	v_and_b32_e32 v119, 0xffff0000, v25
	v_pk_fma_f32 v[180:181], v[128:129], v[100:101], v[180:181]
	v_pk_fma_f32 v[230:231], v[130:131], v[118:119], v[230:231]
	v_pk_mul_f32 v[96:97], v[144:145], s[98:99]
	v_pk_mul_f32 v[98:99], v[178:179], s[98:99]
	v_pk_mul_f32 v[120:121], v[180:181], s[98:99]
	v_pk_mul_f32 v[122:123], v[230:231], s[98:99]
	v_exp_f32_e32 v96, v96
	v_exp_f32_e32 v97, v97
	v_exp_f32_e32 v98, v98
	v_exp_f32_e32 v99, v99
	v_exp_f32_e32 v120, v120
	v_exp_f32_e32 v121, v121
	v_exp_f32_e32 v122, v122
	v_exp_f32_e32 v123, v123
	v_pk_add_f32 v[96:97], v[96:97], s[100:101]
	v_pk_add_f32 v[98:99], v[98:99], s[100:101]
	v_pk_add_f32 v[120:121], v[120:121], s[100:101]
	v_pk_add_f32 v[122:123], v[122:123], s[100:101]
	ds_read_b128 v[132:135], v187 offset:2064
	ds_read_b128 v[112:115], v187 offset:16
	v_rcp_f32_e32 v96, v96
	v_rcp_f32_e32 v97, v97
	v_rcp_f32_e32 v98, v98
	ds_read_b128 v[232:235], v187 offset:528
	v_rcp_f32_e32 v99, v99
	v_rcp_f32_e32 v120, v120
	v_rcp_f32_e32 v121, v121
	v_rcp_f32_e32 v122, v122
	ds_read_b128 v[124:127], v187 offset:1040
	v_rcp_f32_e32 v123, v123
	v_mul_f32_e32 v102, v144, v96
	v_mul_f32_e32 v104, v145, v97
	v_mul_f32_e32 v106, v178, v98
	v_mul_f32_e32 v108, v179, v99
	v_mul_f32_e32 v103, v180, v120
	v_mul_f32_e32 v105, v181, v121
	ds_read_b128 v[128:131], v187 offset:1552
	v_mul_f32_e32 v107, v230, v122
	v_mul_f32_e32 v109, v231, v123
	v_lshlrev_b32_e32 v100, 16, v6
	v_and_b32_e32 v101, 0xffff0000, v6
	v_lshlrev_b32_e32 v118, 16, v7
	v_and_b32_e32 v119, 0xffff0000, v7
	s_waitcnt lgkmcnt(3)
	v_pk_fma_f32 v[144:145], v[112:113], v[100:101], v[132:133]
	v_pk_fma_f32 v[178:179], v[114:115], v[118:119], v[134:135]
	v_lshlrev_b32_e32 v100, 16, v10
	v_and_b32_e32 v101, 0xffff0000, v10
	v_lshlrev_b32_e32 v118, 16, v11
	v_and_b32_e32 v119, 0xffff0000, v11
	s_waitcnt lgkmcnt(2)
	v_pk_fma_f32 v[144:145], v[232:233], v[100:101], v[144:145]
	v_pk_fma_f32 v[178:179], v[234:235], v[118:119], v[178:179]
	v_pk_fma_f32 v[180:181], v[112:113], v[100:101], v[132:133]
	v_pk_fma_f32 v[230:231], v[114:115], v[118:119], v[134:135]
	v_lshlrev_b32_e32 v100, 16, v14
	v_and_b32_e32 v101, 0xffff0000, v14
	v_lshlrev_b32_e32 v118, 16, v15
	v_and_b32_e32 v119, 0xffff0000, v15
	s_waitcnt lgkmcnt(1)
	v_pk_fma_f32 v[144:145], v[124:125], v[100:101], v[144:145]
	v_pk_fma_f32 v[178:179], v[126:127], v[118:119], v[178:179]
	v_pk_fma_f32 v[180:181], v[232:233], v[100:101], v[180:181]
	v_pk_fma_f32 v[230:231], v[234:235], v[118:119], v[230:231]
	v_lshlrev_b32_e32 v100, 16, v18
	v_and_b32_e32 v101, 0xffff0000, v18
	v_lshlrev_b32_e32 v118, 16, v19
	v_and_b32_e32 v119, 0xffff0000, v19
	s_waitcnt lgkmcnt(0)
	v_pk_fma_f32 v[144:145], v[128:129], v[100:101], v[144:145]
	v_pk_fma_f32 v[178:179], v[130:131], v[118:119], v[178:179]
	v_pk_fma_f32 v[180:181], v[124:125], v[100:101], v[180:181]
	v_pk_fma_f32 v[230:231], v[126:127], v[118:119], v[230:231]
	v_lshlrev_b32_e32 v100, 16, v26
	v_and_b32_e32 v101, 0xffff0000, v26
	v_lshlrev_b32_e32 v118, 16, v27
	v_and_b32_e32 v119, 0xffff0000, v27
	v_pk_fma_f32 v[180:181], v[128:129], v[100:101], v[180:181]
	v_pk_fma_f32 v[230:231], v[130:131], v[118:119], v[230:231]
	v_pk_mul_f32 v[96:97], v[144:145], s[98:99]
	v_pk_mul_f32 v[98:99], v[178:179], s[98:99]
	v_pk_mul_f32 v[120:121], v[180:181], s[98:99]
	v_pk_mul_f32 v[122:123], v[230:231], s[98:99]
	v_exp_f32_e32 v96, v96
	v_exp_f32_e32 v97, v97
	v_exp_f32_e32 v98, v98
	v_exp_f32_e32 v99, v99
	v_exp_f32_e32 v120, v120
	v_exp_f32_e32 v121, v121
	v_exp_f32_e32 v122, v122
	v_exp_f32_e32 v123, v123
	v_pk_add_f32 v[96:97], v[96:97], s[100:101]
	v_pk_add_f32 v[98:99], v[98:99], s[100:101]
	v_pk_add_f32 v[120:121], v[120:121], s[100:101]
	v_pk_add_f32 v[122:123], v[122:123], s[100:101]
	v_rcp_f32_e32 v96, v96
	v_rcp_f32_e32 v97, v97
	v_rcp_f32_e32 v98, v98
	v_rcp_f32_e32 v99, v99
	v_rcp_f32_e32 v120, v120
	v_rcp_f32_e32 v121, v121
	v_rcp_f32_e32 v122, v122
	v_rcp_f32_e32 v123, v123
	v_mul_f32_e32 v110, v144, v96
	v_mul_f32_e32 v112, v145, v97
	v_mul_f32_e32 v114, v178, v98
	v_mul_f32_e32 v116, v179, v99
	v_mul_f32_e32 v111, v180, v120
	v_mul_f32_e32 v113, v181, v121
	v_mul_f32_e32 v115, v230, v122
	v_mul_f32_e32 v117, v231, v123
	v_cvt_pk_bf16_f32 v96, v102, v103
	v_cvt_pk_bf16_f32 v97, v104, v105
	v_add_u32_e32 v98, 0xd000, v206
	ds_write2_b32 v98, v96, v97 offset1:36
	v_cvt_pk_bf16_f32 v96, v106, v107
	v_cvt_pk_bf16_f32 v97, v108, v109
	ds_write2_b32 v98, v96, v97 offset0:72 offset1:108
	v_cvt_pk_bf16_f32 v96, v110, v111
	v_cvt_pk_bf16_f32 v97, v112, v113
	ds_write2_b32 v98, v96, v97 offset0:144 offset1:180
	v_cvt_pk_bf16_f32 v96, v114, v115
	v_cvt_pk_bf16_f32 v97, v116, v117
	ds_write2_b32 v98, v96, v97 offset0:216 offset1:252
	ds_read_b128 v[232:235], v187 offset:4608
	ds_read_b128 v[96:99], v187 offset:2560
	ds_read_b128 v[124:127], v187 offset:3072
	ds_read_b128 v[128:131], v187 offset:3584
	ds_read_b128 v[132:135], v187 offset:4096
	s_waitcnt vmcnt(2)
; __device__ __forceinline__ float silu_f(float v) { return v * __builtin_amdgcn_rcpf(1.f + __expf(-v)); }
; __device__ __forceinline__ void conv_rows(const u32x4 (&rawp)[5], const float* wl, float (&o0)[8], float (&o1)[8]) {
;     float raw[5][8];
; #pragma unroll
;     for (int q = 0; q < 5; ++q) unpack8(rawp[q], raw[q]);
; #pragma unroll
;     for (int h = 0; h < 2; ++h) {
;         const f32x4 bv = *(const f32x4*)(wl + 4 * 128 + h * 4);
;         f32x4 a0 = bv, a1 = bv;
; #pragma unroll
;         for (int k = 0; k < 4; ++k) { const f32x4 wv = *(const f32x4*)(wl + k * 128 + h * 4);
; #pragma unroll
;             for (int i = 0; i < 4; ++i) { a0[i] += wv[i] * raw[k][h * 4 + i]; a1[i] += wv[i] * raw[k + 1][h * 4 + i]; } }
; #pragma unroll
;         for (int i = 0; i < 4; ++i) { o0[h * 4 + i] = silu_f(a0[i]); o1[h * 4 + i] = silu_f(a1[i]); }
;         __builtin_amdgcn_sched_barrier(0);
;     }
; }
; __device__ __forceinline__ void phase_ssd(const Params& p, uchar* sm, int j, bf16_t* zx, const float* dtraw, float* ssqb) {
;     ...
;                 conv_rows(rb, wlb, t0, t1);
	v_lshlrev_b32_e32 v144, 16, v20
	v_and_b32_e32 v145, 0xffff0000, v20
	v_lshlrev_b32_e32 v178, 16, v21
	v_and_b32_e32 v179, 0xffff0000, v21
	s_waitcnt lgkmcnt(3)
	v_pk_fma_f32 v[180:181], v[96:97], v[144:145], v[232:233]
	v_pk_fma_f32 v[230:231], v[98:99], v[178:179], v[234:235]
	v_lshlrev_b32_e32 v144, 16, v28
	v_and_b32_e32 v145, 0xffff0000, v28
	v_lshlrev_b32_e32 v178, 16, v29
	v_and_b32_e32 v179, 0xffff0000, v29
	s_waitcnt lgkmcnt(2)
	v_pk_fma_f32 v[180:181], v[124:125], v[144:145], v[180:181]
	v_pk_fma_f32 v[230:231], v[126:127], v[178:179], v[230:231]
	v_pk_fma_f32 v[236:237], v[96:97], v[144:145], v[232:233]
	v_pk_fma_f32 v[238:239], v[98:99], v[178:179], v[234:235]
	v_lshlrev_b32_e32 v144, 16, v32
	v_and_b32_e32 v145, 0xffff0000, v32
	v_lshlrev_b32_e32 v178, 16, v33
	v_and_b32_e32 v179, 0xffff0000, v33
	s_waitcnt lgkmcnt(1)
	v_pk_fma_f32 v[180:181], v[128:129], v[144:145], v[180:181]
	v_pk_fma_f32 v[230:231], v[130:131], v[178:179], v[230:231]
	v_pk_fma_f32 v[236:237], v[124:125], v[144:145], v[236:237]
	v_pk_fma_f32 v[238:239], v[126:127], v[178:179], v[238:239]
	v_lshlrev_b32_e32 v144, 16, v36
	v_and_b32_e32 v145, 0xffff0000, v36
	v_lshlrev_b32_e32 v178, 16, v37
	v_and_b32_e32 v179, 0xffff0000, v37
	s_waitcnt lgkmcnt(0)
	v_pk_fma_f32 v[180:181], v[132:133], v[144:145], v[180:181]
	v_pk_fma_f32 v[230:231], v[134:135], v[178:179], v[230:231]
	v_pk_fma_f32 v[236:237], v[128:129], v[144:145], v[236:237]
	v_pk_fma_f32 v[238:239], v[130:131], v[178:179], v[238:239]
	v_lshlrev_b32_e32 v144, 16, v40
	v_and_b32_e32 v145, 0xffff0000, v40
	v_lshlrev_b32_e32 v178, 16, v41
	v_and_b32_e32 v179, 0xffff0000, v41
	v_pk_fma_f32 v[236:237], v[132:133], v[144:145], v[236:237]
	v_pk_fma_f32 v[238:239], v[134:135], v[178:179], v[238:239]
	v_pk_mul_f32 v[96:97], v[180:181], s[98:99]
	v_pk_mul_f32 v[98:99], v[230:231], s[98:99]
	v_pk_mul_f32 v[124:125], v[236:237], s[98:99]
	v_pk_mul_f32 v[126:127], v[238:239], s[98:99]
	v_exp_f32_e32 v96, v96
	v_exp_f32_e32 v97, v97
	v_exp_f32_e32 v98, v98
	v_exp_f32_e32 v99, v99
	v_exp_f32_e32 v124, v124
	v_exp_f32_e32 v125, v125
	v_exp_f32_e32 v126, v126
	v_exp_f32_e32 v127, v127
	v_pk_add_f32 v[96:97], v[96:97], s[100:101]
	v_pk_add_f32 v[98:99], v[98:99], s[100:101]
	v_pk_add_f32 v[124:125], v[124:125], s[100:101]
	v_pk_add_f32 v[126:127], v[126:127], s[100:101]
	ds_read_b128 v[232:235], v187 offset:4624
	ds_read_b128 v[120:123], v187 offset:2576
	v_rcp_f32_e32 v96, v96
	v_rcp_f32_e32 v97, v97
	v_rcp_f32_e32 v98, v98
	ds_read_b128 v[248:251], v187 offset:3088
	v_rcp_f32_e32 v99, v99
	v_rcp_f32_e32 v124, v124
	v_rcp_f32_e32 v125, v125
	v_rcp_f32_e32 v126, v126
	ds_read_b128 v[128:131], v187 offset:3600
	v_rcp_f32_e32 v127, v127
	v_mul_f32_e32 v139, v180, v96
	v_mul_f32_e32 v229, v181, v97
	v_mul_f32_e32 v241, v230, v98
	v_mul_f32_e32 v243, v231, v99
	v_mul_f32_e32 v170, v236, v124
	v_mul_f32_e32 v240, v237, v125
	ds_read_b128 v[132:135], v187 offset:4112
	v_mul_f32_e32 v242, v238, v126
	v_mul_f32_e32 v244, v239, v127
	v_lshlrev_b32_e32 v144, 16, v22
	v_and_b32_e32 v145, 0xffff0000, v22
	v_lshlrev_b32_e32 v178, 16, v23
	v_and_b32_e32 v179, 0xffff0000, v23
	s_waitcnt lgkmcnt(3)
	v_pk_fma_f32 v[180:181], v[120:121], v[144:145], v[232:233]
	v_pk_fma_f32 v[230:231], v[122:123], v[178:179], v[234:235]
	v_lshlrev_b32_e32 v144, 16, v30
	v_and_b32_e32 v145, 0xffff0000, v30
	v_lshlrev_b32_e32 v178, 16, v31
	v_and_b32_e32 v179, 0xffff0000, v31
	s_waitcnt lgkmcnt(2)
	v_pk_fma_f32 v[180:181], v[248:249], v[144:145], v[180:181]
	v_pk_fma_f32 v[230:231], v[250:251], v[178:179], v[230:231]
	v_pk_fma_f32 v[236:237], v[120:121], v[144:145], v[232:233]
	v_pk_fma_f32 v[238:239], v[122:123], v[178:179], v[234:235]
	v_lshlrev_b32_e32 v144, 16, v34
	v_and_b32_e32 v145, 0xffff0000, v34
	v_lshlrev_b32_e32 v178, 16, v35
	v_and_b32_e32 v179, 0xffff0000, v35
	s_waitcnt lgkmcnt(1)
	v_pk_fma_f32 v[180:181], v[128:129], v[144:145], v[180:181]
	v_pk_fma_f32 v[230:231], v[130:131], v[178:179], v[230:231]
	v_pk_fma_f32 v[236:237], v[248:249], v[144:145], v[236:237]
	v_pk_fma_f32 v[238:239], v[250:251], v[178:179], v[238:239]
	v_lshlrev_b32_e32 v144, 16, v38
	v_and_b32_e32 v145, 0xffff0000, v38
	v_lshlrev_b32_e32 v178, 16, v39
	v_and_b32_e32 v179, 0xffff0000, v39
	s_waitcnt lgkmcnt(0)
; __device__ __forceinline__ unsigned pk2(float lo, float hi) { unsigned r; asm("v_cvt_pk_bf16_f32 %0, %1, %2" : "=v"(r) : "v"(lo), "v"(hi)); return r; }
; __device__ __forceinline__ u32x4 pack8(const float (&o)[8]) { u32x4 r; r.x = pk2(o[0], o[1]); r.y = pk2(o[2], o[3]); r.z = pk2(o[4], o[5]); r.w = pk2(o[6], o[7]); return r; }
; __device__ __forceinline__ float silu_f(float v) { return v * __builtin_amdgcn_rcpf(1.f + __expf(-v)); }
; __device__ __forceinline__ void conv_rows(const u32x4 (&rawp)[5], const float* wl, float (&o0)[8], float (&o1)[8]) {
;     float raw[5][8];
; #pragma unroll
;     for (int q = 0; q < 5; ++q) unpack8(rawp[q], raw[q]);
; #pragma unroll
;     for (int h = 0; h < 2; ++h) {
;         const f32x4 bv = *(const f32x4*)(wl + 4 * 128 + h * 4);
;         f32x4 a0 = bv, a1 = bv;
; #pragma unroll
;         for (int k = 0; k < 4; ++k) { const f32x4 wv = *(const f32x4*)(wl + k * 128 + h * 4);
; #pragma unroll
;             for (int i = 0; i < 4; ++i) { a0[i] += wv[i] * raw[k][h * 4 + i]; a1[i] += wv[i] * raw[k + 1][h * 4 + i]; } }
; #pragma unroll
;         for (int i = 0; i < 4; ++i) { o0[h * 4 + i] = silu_f(a0[i]); o1[h * 4 + i] = silu_f(a1[i]); }
;         __builtin_amdgcn_sched_barrier(0);
;     }
; }
; __device__ __forceinline__ void phase_ssd(const Params& p, uchar* sm, int j, bf16_t* zx, const float* dtraw, float* ssqb) {
;     ...
;                 conv_rows(rb, wlb, t0, t1);
;                 __builtin_amdgcn_sched_barrier(0);
;                 *(u32x4*)(sm + L_B + (2 * lp) * RS_CB + c8 * 16) = pack8(t0);
;                 *(u32x4*)(sm + L_B + (2 * lp + 1) * RS_CB + c8 * 16) = pack8(t1);
; #pragma unroll
;                 for (int i = 0; i < 8; ++i) *(unsigned*)(sm + L_BT + (c8 * 8 + i) * RS_T + ((lp ^ swz) * 4)) = pk2(t0[i], t1[i]);
;                 __builtin_amdgcn_sched_barrier(0);
;                 conv_rows(rc, wlc, t0, t1);
	v_pk_fma_f32 v[180:181], v[132:133], v[144:145], v[180:181]
	v_pk_fma_f32 v[230:231], v[134:135], v[178:179], v[230:231]
	v_pk_fma_f32 v[236:237], v[128:129], v[144:145], v[236:237]
	v_pk_fma_f32 v[238:239], v[130:131], v[178:179], v[238:239]
	v_lshlrev_b32_e32 v144, 16, v42
	v_and_b32_e32 v145, 0xffff0000, v42
	v_lshlrev_b32_e32 v178, 16, v43
	v_and_b32_e32 v179, 0xffff0000, v43
	v_pk_fma_f32 v[236:237], v[132:133], v[144:145], v[236:237]
	v_pk_fma_f32 v[238:239], v[134:135], v[178:179], v[238:239]
	v_pk_mul_f32 v[96:97], v[180:181], s[98:99]
	v_pk_mul_f32 v[98:99], v[230:231], s[98:99]
	v_pk_mul_f32 v[124:125], v[236:237], s[98:99]
	v_pk_mul_f32 v[126:127], v[238:239], s[98:99]
	v_exp_f32_e32 v96, v96
	v_exp_f32_e32 v97, v97
	v_exp_f32_e32 v98, v98
	v_exp_f32_e32 v99, v99
	v_exp_f32_e32 v124, v124
	v_exp_f32_e32 v125, v125
	v_exp_f32_e32 v126, v126
	v_exp_f32_e32 v127, v127
	v_pk_add_f32 v[96:97], v[96:97], s[100:101]
	v_pk_add_f32 v[98:99], v[98:99], s[100:101]
	v_pk_add_f32 v[124:125], v[124:125], s[100:101]
	v_pk_add_f32 v[126:127], v[126:127], s[100:101]
	v_rcp_f32_e32 v96, v96
	v_rcp_f32_e32 v97, v97
	v_rcp_f32_e32 v98, v98
	v_rcp_f32_e32 v99, v99
	v_rcp_f32_e32 v124, v124
	v_rcp_f32_e32 v125, v125
	v_rcp_f32_e32 v126, v126
	v_rcp_f32_e32 v127, v127
	v_mul_f32_e32 v119, v180, v96
	v_mul_f32_e32 v100, v181, v97
	v_mul_f32_e32 v120, v230, v98
	v_mul_f32_e32 v101, v231, v99
	v_mul_f32_e32 v121, v236, v124
	v_mul_f32_e32 v122, v237, v125
	v_mul_f32_e32 v118, v238, v126
	v_mul_f32_e32 v123, v239, v127
	v_cvt_pk_bf16_f32 v96, v139, v229
	v_cvt_pk_bf16_f32 v97, v241, v243
	v_cvt_pk_bf16_f32 v98, v119, v100
	v_cvt_pk_bf16_f32 v99, v120, v101
	ds_write_b128 v207, v[96:99] offset:17408
	v_cvt_pk_bf16_f32 v96, v170, v240
	v_cvt_pk_bf16_f32 v97, v242, v244
	v_cvt_pk_bf16_f32 v98, v121, v122
	v_cvt_pk_bf16_f32 v99, v118, v123
	ds_write_b128 v208, v[96:99] offset:17408
	v_cvt_pk_bf16_f32 v96, v139, v170
	v_cvt_pk_bf16_f32 v97, v229, v240
	v_add_u32_e32 v98, 0x8800, v206
	ds_write2_b32 v98, v96, v97 offset1:36
	v_cvt_pk_bf16_f32 v96, v241, v242
	v_cvt_pk_bf16_f32 v97, v243, v244
	ds_write2_b32 v98, v96, v97 offset0:72 offset1:108
	v_cvt_pk_bf16_f32 v96, v119, v121
	v_cvt_pk_bf16_f32 v97, v100, v122
	ds_write2_b32 v98, v96, v97 offset0:144 offset1:180
	v_cvt_pk_bf16_f32 v96, v120, v118
	v_cvt_pk_bf16_f32 v97, v101, v123
	ds_write2_b32 v98, v96, v97 offset0:216 offset1:252
	ds_read_b128 v[236:239], v187 offset:7168
	ds_read_b128 v[124:127], v187 offset:5120
	ds_read_b128 v[128:131], v187 offset:5632
	ds_read_b128 v[132:135], v187 offset:6144
	ds_read_b128 v[232:235], v187 offset:6656
	v_lshlrev_b32_e32 v96, 16, v44
	v_and_b32_e32 v97, 0xffff0000, v44
	v_lshlrev_b32_e32 v144, 16, v45
	v_and_b32_e32 v145, 0xffff0000, v45
	s_waitcnt lgkmcnt(3)
	v_pk_fma_f32 v[178:179], v[124:125], v[96:97], v[236:237]
	v_pk_fma_f32 v[180:181], v[126:127], v[144:145], v[238:239]
	v_lshlrev_b32_e32 v96, 16, v48
	v_and_b32_e32 v97, 0xffff0000, v48
	v_lshlrev_b32_e32 v144, 16, v49
	v_and_b32_e32 v145, 0xffff0000, v49
	s_waitcnt lgkmcnt(2)
	v_pk_fma_f32 v[178:179], v[128:129], v[96:97], v[178:179]
	v_pk_fma_f32 v[180:181], v[130:131], v[144:145], v[180:181]
	v_pk_fma_f32 v[230:231], v[124:125], v[96:97], v[236:237]
	v_pk_fma_f32 v[246:247], v[126:127], v[144:145], v[238:239]
	v_lshlrev_b32_e32 v96, 16, v52
	v_and_b32_e32 v97, 0xffff0000, v52
	v_lshlrev_b32_e32 v144, 16, v53
	v_and_b32_e32 v145, 0xffff0000, v53
	s_waitcnt lgkmcnt(1)
	v_pk_fma_f32 v[178:179], v[132:133], v[96:97], v[178:179]
	v_pk_fma_f32 v[180:181], v[134:135], v[144:145], v[180:181]
	v_pk_fma_f32 v[230:231], v[128:129], v[96:97], v[230:231]
	v_pk_fma_f32 v[246:247], v[130:131], v[144:145], v[246:247]
	v_lshlrev_b32_e32 v96, 16, v56
	v_and_b32_e32 v97, 0xffff0000, v56
	v_lshlrev_b32_e32 v144, 16, v57
	v_and_b32_e32 v145, 0xffff0000, v57
	s_waitcnt lgkmcnt(0)
	v_pk_fma_f32 v[178:179], v[232:233], v[96:97], v[178:179]
	v_pk_fma_f32 v[180:181], v[234:235], v[144:145], v[180:181]
	v_pk_fma_f32 v[230:231], v[132:133], v[96:97], v[230:231]
	v_pk_fma_f32 v[246:247], v[134:135], v[144:145], v[246:247]
	v_lshlrev_b32_e32 v96, 16, v60
	v_and_b32_e32 v97, 0xffff0000, v60
	v_lshlrev_b32_e32 v144, 16, v61
	v_and_b32_e32 v145, 0xffff0000, v61
	v_pk_fma_f32 v[230:231], v[232:233], v[96:97], v[230:231]
	v_pk_fma_f32 v[246:247], v[234:235], v[144:145], v[246:247]
	v_pk_mul_f32 v[124:125], v[178:179], s[98:99]
	v_pk_mul_f32 v[126:127], v[180:181], s[98:99]
	v_pk_mul_f32 v[128:129], v[230:231], s[98:99]
	v_pk_mul_f32 v[130:131], v[246:247], s[98:99]
	v_exp_f32_e32 v124, v124
	v_exp_f32_e32 v125, v125
	v_exp_f32_e32 v126, v126
	v_exp_f32_e32 v127, v127
	v_exp_f32_e32 v128, v128
	v_exp_f32_e32 v129, v129
	v_exp_f32_e32 v130, v130
	v_exp_f32_e32 v131, v131
	v_pk_add_f32 v[124:125], v[124:125], s[100:101]
	v_pk_add_f32 v[126:127], v[126:127], s[100:101]
	v_pk_add_f32 v[128:129], v[128:129], s[100:101]
	v_pk_add_f32 v[130:131], v[130:131], s[100:101]
	ds_read_b128 v[236:239], v187 offset:7184
	ds_read_b128 v[120:123], v187 offset:5136
	v_rcp_f32_e32 v124, v124
	v_rcp_f32_e32 v125, v125
	v_rcp_f32_e32 v126, v126
	ds_read_b128 v[248:251], v187 offset:5648
	v_rcp_f32_e32 v127, v127
	v_rcp_f32_e32 v128, v128
	v_rcp_f32_e32 v129, v129
	v_rcp_f32_e32 v130, v130
	ds_read_b128 v[132:135], v187 offset:6160
	v_rcp_f32_e32 v131, v131
	v_mul_f32_e32 v139, v178, v124
	v_mul_f32_e32 v229, v179, v125
	v_mul_f32_e32 v241, v180, v126
	v_mul_f32_e32 v243, v181, v127
	v_mul_f32_e32 v170, v230, v128
	v_mul_f32_e32 v240, v231, v129
	ds_read_b128 v[232:235], v187 offset:6672
	v_mul_f32_e32 v242, v246, v130
	v_mul_f32_e32 v244, v247, v131
	v_lshlrev_b32_e32 v96, 16, v46
	v_and_b32_e32 v97, 0xffff0000, v46
	v_lshlrev_b32_e32 v144, 16, v47
	v_and_b32_e32 v145, 0xffff0000, v47
	s_waitcnt lgkmcnt(3)
; __device__ __forceinline__ u32x4 pack8(const float (&o)[8]) { u32x4 r; r.x = pk2(o[0], o[1]); r.y = pk2(o[2], o[3]); r.z = pk2(o[4], o[5]); r.w = pk2(o[6], o[7]); return r; }
; __device__ __forceinline__ void phase_ssd(const Params& p, uchar* sm, int j, bf16_t* zx, const float* dtraw, float* ssqb) {
;     ...
;                 conv_rows(rc, wlc, t0, t1);
;                 __builtin_amdgcn_sched_barrier(0);
;                 *(u32x4*)(sm + L_C + (2 * lp) * RS_CB + c8 * 16) = pack8(t0);
;                 *(u32x4*)(sm + L_C + (2 * lp + 1) * RS_CB + c8 * 16) = pack8(t1);
;             }
;             const u32x4 xp0 = pack8(xo0), xp1 = pack8(xo1);
;             bf16_t* zc = zx + (size_t)zrow0 * LDZ;
;             if (c + 1 < 32) { const bf16_t* zb = zc + 64 * LDZ;
;                 load_raw(zb + 2048 + colx, toff, false, 2 * lp, rx); }
	v_pk_fma_f32 v[178:179], v[120:121], v[96:97], v[236:237]
	v_pk_fma_f32 v[180:181], v[122:123], v[144:145], v[238:239]
	v_lshlrev_b32_e32 v96, 16, v50
	v_and_b32_e32 v97, 0xffff0000, v50
	v_lshlrev_b32_e32 v144, 16, v51
	v_and_b32_e32 v145, 0xffff0000, v51
	s_waitcnt lgkmcnt(2)
	v_pk_fma_f32 v[178:179], v[248:249], v[96:97], v[178:179]
	v_pk_fma_f32 v[180:181], v[250:251], v[144:145], v[180:181]
	v_pk_fma_f32 v[230:231], v[120:121], v[96:97], v[236:237]
	v_pk_fma_f32 v[246:247], v[122:123], v[144:145], v[238:239]
	v_lshlrev_b32_e32 v96, 16, v54
	v_and_b32_e32 v97, 0xffff0000, v54
	v_lshlrev_b32_e32 v144, 16, v55
	v_and_b32_e32 v145, 0xffff0000, v55
	s_waitcnt lgkmcnt(1)
	v_pk_fma_f32 v[178:179], v[132:133], v[96:97], v[178:179]
	v_pk_fma_f32 v[180:181], v[134:135], v[144:145], v[180:181]
	v_pk_fma_f32 v[230:231], v[248:249], v[96:97], v[230:231]
	v_pk_fma_f32 v[246:247], v[250:251], v[144:145], v[246:247]
	v_lshlrev_b32_e32 v96, 16, v58
	v_and_b32_e32 v97, 0xffff0000, v58
	v_lshlrev_b32_e32 v144, 16, v59
	v_and_b32_e32 v145, 0xffff0000, v59
	s_waitcnt lgkmcnt(0)
	v_pk_fma_f32 v[178:179], v[232:233], v[96:97], v[178:179]
	v_pk_fma_f32 v[180:181], v[234:235], v[144:145], v[180:181]
	v_pk_fma_f32 v[230:231], v[132:133], v[96:97], v[230:231]
	v_pk_fma_f32 v[246:247], v[134:135], v[144:145], v[246:247]
	v_lshlrev_b32_e32 v96, 16, v62
	v_and_b32_e32 v97, 0xffff0000, v62
	v_lshlrev_b32_e32 v144, 16, v63
	v_and_b32_e32 v145, 0xffff0000, v63
	v_pk_fma_f32 v[230:231], v[232:233], v[96:97], v[230:231]
	v_pk_fma_f32 v[246:247], v[234:235], v[144:145], v[246:247]
	v_pk_mul_f32 v[124:125], v[178:179], s[98:99]
	v_pk_mul_f32 v[126:127], v[180:181], s[98:99]
	v_pk_mul_f32 v[128:129], v[230:231], s[98:99]
	v_pk_mul_f32 v[130:131], v[246:247], s[98:99]
	v_exp_f32_e32 v124, v124
	v_exp_f32_e32 v125, v125
	v_exp_f32_e32 v126, v126
	v_exp_f32_e32 v127, v127
	v_exp_f32_e32 v128, v128
	v_exp_f32_e32 v129, v129
	v_exp_f32_e32 v130, v130
	v_exp_f32_e32 v131, v131
	v_pk_add_f32 v[124:125], v[124:125], s[100:101]
	v_pk_add_f32 v[126:127], v[126:127], s[100:101]
	v_pk_add_f32 v[128:129], v[128:129], s[100:101]
	v_pk_add_f32 v[130:131], v[130:131], s[100:101]
	v_rcp_f32_e32 v124, v124
	v_rcp_f32_e32 v125, v125
	v_rcp_f32_e32 v126, v126
	v_rcp_f32_e32 v127, v127
	v_rcp_f32_e32 v128, v128
	v_rcp_f32_e32 v129, v129
	v_rcp_f32_e32 v130, v130
	v_rcp_f32_e32 v131, v131
	v_mul_f32_e32 v119, v178, v124
	v_mul_f32_e32 v99, v179, v125
	v_mul_f32_e32 v120, v180, v126
	v_mul_f32_e32 v101, v181, v127
	v_mul_f32_e32 v121, v230, v128
	v_mul_f32_e32 v122, v231, v129
	v_mul_f32_e32 v100, v246, v130
	v_mul_f32_e32 v118, v247, v131
	v_readlane_b32 s60, v254, 0
	s_cmp_lg_u32 s83, 1
	v_readlane_b32 s66, v254, 6
	v_readlane_b32 s67, v254, 7
	v_cvt_pk_bf16_f32 v96, v139, v229
	v_cvt_pk_bf16_f32 v97, v241, v243
	v_cvt_pk_bf16_f32 v98, v119, v99
	v_cvt_pk_bf16_f32 v99, v120, v101
	v_cvt_pk_bf16_f32 v235, v102, v104
	v_cvt_pk_bf16_f32 v231, v103, v105
	s_cselect_b64 s[0:1], -1, 0
	s_cmp_eq_u32 s83, 1
	v_lshl_add_u64 v[104:105], s[66:67], 0, v[174:175]
	ds_write_b128 v207, v[96:99]
	v_cvt_pk_bf16_f32 v96, v170, v240
	v_cvt_pk_bf16_f32 v97, v242, v244
	v_cvt_pk_bf16_f32 v98, v121, v122
	v_cvt_pk_bf16_f32 v99, v100, v118
	ds_write_b128 v208, v[96:99]
	v_cvt_pk_bf16_f32 v233, v106, v108
	v_cvt_pk_bf16_f32 v236, v110, v112
	v_cvt_pk_bf16_f32 v234, v114, v116
	v_cvt_pk_bf16_f32 v229, v107, v109
	v_cvt_pk_bf16_f32 v232, v111, v113
	v_cvt_pk_bf16_f32 v230, v115, v117
	v_readlane_b32 s61, v254, 1
	v_readlane_b32 s62, v254, 2
	v_readlane_b32 s63, v254, 3
	v_readlane_b32 s64, v254, 4
	v_readlane_b32 s65, v254, 5
	s_cbranch_scc1 .LBB0_468
	v_add_co_u32_e32 v4, vcc, 0x64d5000, v104
	s_nop 1
	v_addc_co_u32_e32 v5, vcc, 0, v105, vcc
	v_add_co_u32_e32 v8, vcc, 0x64d8000, v104
	s_nop 1
	v_addc_co_u32_e32 v9, vcc, 0, v105, vcc
	v_add_co_u32_e32 v12, vcc, 0x64db000, v104
	global_load_dwordx4 v[4:7], v[4:5], off offset:3712
	s_nop 0
	global_load_dwordx4 v[8:11], v[8:9], off offset:3840
	v_addc_co_u32_e32 v13, vcc, 0, v105, vcc
	v_add_co_u32_e32 v16, vcc, 0x64df000, v104
	s_nop 1
	v_addc_co_u32_e32 v17, vcc, 0, v105, vcc
	v_add_co_u32_e32 v24, vcc, 0x64e2000, v104
	global_load_dwordx4 v[12:15], v[12:13], off offset:3968
	s_nop 0
	global_load_dwordx4 v[16:19], v[16:17], off
	v_addc_co_u32_e32 v25, vcc, 0, v105, vcc
	global_load_dwordx4 v[24:27], v[24:25], off offset:128

; __global__ void __launch_bounds__(512, 2) fwd_megakernel(Params p) {
;     extern __shared__ __attribute__((aligned(16))) uchar smem[];
	.amdhsa_kernel _Z14fwd_megakernel6Params
		.amdhsa_group_segment_fixed_size 0
		.amdhsa_private_segment_fixed_size 0
		.amdhsa_kernarg_size 424
		.amdhsa_user_sgpr_count 2
		.amdhsa_user_sgpr_dispatch_ptr 0
		.amdhsa_user_sgpr_queue_ptr 0
		.amdhsa_user_sgpr_kernarg_segment_ptr 1
		.amdhsa_user_sgpr_dispatch_id 0
		.amdhsa_user_sgpr_kernarg_preload_length 0
		.amdhsa_user_sgpr_kernarg_preload_offset 0
		.amdhsa_user_sgpr_private_segment_size 0
		.amdhsa_uses_dynamic_stack 0
		.amdhsa_enable_private_segment 0
		.amdhsa_system_sgpr_workgroup_id_x 1
		.amdhsa_system_sgpr_workgroup_id_y 0
		.amdhsa_system_sgpr_workgroup_id_z 0
		.amdhsa_system_sgpr_workgroup_info 0
		.amdhsa_system_vgpr_workitem_id 2
		.amdhsa_next_free_vgpr 256
		.amdhsa_next_free_sgpr 102
		.amdhsa_accum_offset 256
		.amdhsa_reserve_vcc 1
		.amdhsa_float_round_mode_32 0
		.amdhsa_float_round_mode_16_64 0
		.amdhsa_float_denorm_mode_32 3
		.amdhsa_float_denorm_mode_16_64 3
		.amdhsa_dx10_clamp 1
		.amdhsa_ieee_mode 1
		.amdhsa_fp16_overflow 0
		.amdhsa_tg_split 0
		.amdhsa_exception_fp_ieee_invalid_op 0
		.amdhsa_exception_fp_denorm_src 0
		.amdhsa_exception_fp_ieee_div_zero 0
		.amdhsa_exception_fp_ieee_overflow 0
		.amdhsa_exception_fp_ieee_underflow 0
		.amdhsa_exception_fp_ieee_inexact 0
		.amdhsa_exception_int_div_zero 0
	.end_amdhsa_kernel

; __global__ void __launch_bounds__(512, 2) fwd_megakernel(Params p) {
;     extern __shared__ __attribute__((aligned(16))) uchar smem[];
amdhsa.kernels:
  - .agpr_count:     0
    .args:
      - .offset:         0
        .size:           168
        .value_kind:     by_value
      - .offset:         168
        .size:           4
        .value_kind:     hidden_block_count_x
      - .offset:         172
        .size:           4
        .value_kind:     hidden_block_count_y
      - .offset:         176
        .size:           4
        .value_kind:     hidden_block_count_z
      - .offset:         180
        .size:           2
        .value_kind:     hidden_group_size_x
      - .offset:         182
        .size:           2
        .value_kind:     hidden_group_size_y
      - .offset:         184
        .size:           2
        .value_kind:     hidden_group_size_z
      - .offset:         186
        .size:           2
        .value_kind:     hidden_remainder_x
      - .offset:         188
        .size:           2
        .value_kind:     hidden_remainder_y
      - .offset:         190
        .size:           2
        .value_kind:     hidden_remainder_z
      - .offset:         208
        .size:           8
        .value_kind:     hidden_global_offset_x
      - .offset:         216
        .size:           8
        .value_kind:     hidden_global_offset_y
      - .offset:         224
        .size:           8
        .value_kind:     hidden_global_offset_z
      - .offset:         232
        .size:           2
        .value_kind:     hidden_grid_dims
      - .offset:         256
        .size:           8
        .value_kind:     hidden_multigrid_sync_arg
      - .offset:         288
        .size:           4
        .value_kind:     hidden_dynamic_lds_size
    .group_segment_fixed_size: 0
    .kernarg_segment_align: 8
    .kernarg_segment_size: 424
    .language:       OpenCL C
    .language_version:
      - 2
      - 0
    .max_flat_workgroup_size: 512
    .name:           _Z14fwd_megakernel6Params
    .private_segment_fixed_size: 0
    .sgpr_count:     108
    .sgpr_spill_count: 189
    .symbol:         _Z14fwd_megakernel6Params.kd
    .uniform_work_group_size: 1
    .uses_dynamic_stack: false
    .vgpr_count:     256
    .vgpr_spill_count: 0
    .wavefront_size: 64
